# adds: nt cache policy on the residual-GEMM (AOUT/MOUT/DOWN) epilogue stores
# baseline (speedup 1.0000x reference)
; __device__ __forceinline__ unsigned cvt_pk_bf16(float lo, float hi) { unsigned r; asm volatile("v_cvt_pk_bf16_f32 %0, %1, %2" : "=v"(r) : "v"(lo), "v"(hi)); return r; }
;     __device__ __forceinline__ void operator()(const f32x4 (&acc)[2][2][4][2], const Unit& u, int wr, int wc, int fr, int fq) const {
;         const int row0 = row_base + u.pm * BM + wr * 64 + fr;
;         const int col0 = u.pn * BM + wc * 32 + 8 * fq;
;         u32x4 pre[2][4][2];
; #pragma unroll
;         for (int ai = 0; ai < 2; ++ai)
; #pragma unroll
;             for (int m = 0; m < 4; ++m)
; #pragma unroll
;                 for (int bj = 0; bj < 2; ++bj) pre[ai][m][bj] = *(const u32x4*)(XB + (size_t)(row0 + ai * HALF + m * 16) * 1024 + col0 + bj * HALF);
; #pragma unroll
;         for (int ai = 0; ai < 2; ++ai)
; #pragma unroll
;             for (int m = 0; m < 4; ++m) {
;                 const int r = row0 + ai * HALF + m * 16; const size_t off = (size_t)r * 1024 + col0; float s = 0.f;
; #pragma unroll
;                 for (int bj = 0; bj < 2; ++bj) {
;                     const u32x4 bw = pre[ai][m][bj];
;                     f32x4 b0, b1; b0[0] = __builtin_bit_cast(float, bw.x << 16); b0[1] = __builtin_bit_cast(float, bw.x & 0xffff0000u); b0[2] = __builtin_bit_cast(float, bw.y << 16); b0[3] = __builtin_bit_cast(float, bw.y & 0xffff0000u);
;                     b1[0] = __builtin_bit_cast(float, bw.z << 16); b1[1] = __builtin_bit_cast(float, bw.z & 0xffff0000u); b1[2] = __builtin_bit_cast(float, bw.w << 16); b1[3] = __builtin_bit_cast(float, bw.w & 0xffff0000u);
;                     const f32x4 v0 = b0 + acc[ai][bj][m][0], v1 = b1 + acc[ai][bj][m][1];
;                     if (X) { *(f32x4*)(X + off + bj * HALF) = v0; *(f32x4*)(X + off + bj * HALF + 4) = v1; }
;                     s += (v0[0] * v0[0] + v0[1] * v0[1]) + (v0[2] * v0[2] + v0[3] * v0[3]) + (v1[0] * v1[0] + v1[1] * v1[1]) + (v1[2] * v1[2] + v1[3] * v1[3]);
;                     u32x4 w; w.x = cvt_pk_bf16(v0[0], v0[1]); w.y = cvt_pk_bf16(v0[2], v0[3]); w.z = cvt_pk_bf16(v1[0], v1[1]); w.w = cvt_pk_bf16(v1[2], v1[3]);
;                     *(u32x4*)(XB + off + bj * HALF) = w; }
;                 s = x16_sum(s); s = x32_sum(s);
;                 if (fq == 0 && ssn) atomicAdd((unsigned long long*)(ssn + r), (unsigned long long)__float2ll_rn(s * 1048576.0f));
.LBB0_251:
	v_lshl_add_u32 v220, s94, 8, v237
	v_lshl_or_b32 v204, s78, 8, v238
	v_readlane_b32 s40, v252, 8
	v_ashrrev_i32_e32 v205, 31, v204
	v_readlane_b32 s41, v252, 9
	v_ashrrev_i32_e32 v221, 31, v220
	v_lshlrev_b64 v[80:81], 11, v[220:221]
	v_lshl_add_u64 v[202:203], v[204:205], 1, s[40:41]
	v_or_b32_e32 v218, 16, v220
	v_lshl_add_u64 v[80:81], v[202:203], 0, v[80:81]
	v_ashrrev_i32_e32 v219, 31, v218
	global_load_dwordx4 v[242:245], v[80:81], off
	global_load_dwordx4 v[186:189], v[80:81], off offset:256
	v_lshlrev_b64 v[80:81], 11, v[218:219]
	v_or_b32_e32 v216, 32, v220
	v_lshl_add_u64 v[80:81], v[202:203], 0, v[80:81]
	v_ashrrev_i32_e32 v217, 31, v216
	global_load_dwordx4 v[182:185], v[80:81], off
	global_load_dwordx4 v[178:181], v[80:81], off offset:256
	v_lshlrev_b64 v[80:81], 11, v[216:217]
	v_or_b32_e32 v214, 48, v220
	v_lshl_add_u64 v[80:81], v[202:203], 0, v[80:81]
	v_ashrrev_i32_e32 v215, 31, v214
	global_load_dwordx4 v[174:177], v[80:81], off
	global_load_dwordx4 v[170:173], v[80:81], off offset:256
	v_lshlrev_b64 v[80:81], 11, v[214:215]
	v_add_u32_e32 v212, 0x80, v220
	v_lshl_add_u64 v[80:81], v[202:203], 0, v[80:81]
	v_ashrrev_i32_e32 v213, 31, v212
	global_load_dwordx4 v[166:169], v[80:81], off
	global_load_dwordx4 v[162:165], v[80:81], off offset:256
	v_lshlrev_b64 v[80:81], 11, v[212:213]
	v_add_u32_e32 v210, 0x90, v220
	v_lshl_add_u64 v[80:81], v[202:203], 0, v[80:81]
	v_ashrrev_i32_e32 v211, 31, v210
	global_load_dwordx4 v[158:161], v[80:81], off
	global_load_dwordx4 v[146:149], v[80:81], off offset:256
	v_lshlrev_b64 v[80:81], 11, v[210:211]
	v_add_u32_e32 v208, 0xa0, v220
	v_lshl_add_u64 v[80:81], v[202:203], 0, v[80:81]
	v_ashrrev_i32_e32 v209, 31, v208
	global_load_dwordx4 v[134:137], v[80:81], off
	global_load_dwordx4 v[122:125], v[80:81], off offset:256
	v_lshlrev_b64 v[80:81], 11, v[208:209]
	v_add_u32_e32 v206, 0xb0, v220
	v_lshl_add_u64 v[80:81], v[202:203], 0, v[80:81]
	v_ashrrev_i32_e32 v207, 31, v206
	global_load_dwordx4 v[108:111], v[80:81], off
	global_load_dwordx4 v[100:103], v[80:81], off offset:256
	v_lshlrev_b64 v[80:81], 11, v[206:207]
	v_lshl_add_u64 v[80:81], v[202:203], 0, v[80:81]
	global_load_dwordx4 v[84:87], v[80:81], off
	s_nop 0
	global_load_dwordx4 v[80:83], v[80:81], off offset:256
	v_cndmask_b32_e64 v222, 0, 1, s[60:61]
	v_cmp_ne_u32_e64 s[40:41], 1, v222
	v_lshlrev_b64 v[222:223], 10, v[220:221]
	v_lshl_add_u64 v[224:225], v[222:223], 0, v[204:205]
	s_andn2_b64 vcc, exec, s[60:61]
	v_lshl_add_u64 v[224:225], v[224:225], 2, s[48:49]
	v_readlane_b32 s92, v250, 10
	s_waitcnt vmcnt(0)
	v_lshlrev_b32_e32 v246, 16, v242
	v_and_b32_e32 v247, 0xffff0000, v242
	v_lshlrev_b32_e32 v242, 16, v243
	v_and_b32_e32 v243, 0xffff0000, v243
	v_lshlrev_b32_e32 v248, 16, v244
	v_and_b32_e32 v249, 0xffff0000, v244
	v_lshlrev_b32_e32 v244, 16, v245
	v_and_b32_e32 v245, 0xffff0000, v245
	v_pk_add_f32 v[156:157], v[156:157], v[242:243]
	v_pk_add_f32 v[154:155], v[154:155], v[246:247]
	v_pk_add_f32 v[152:153], v[152:153], v[244:245]
	v_pk_add_f32 v[150:151], v[150:151], v[248:249]
	s_cbranch_vccnz .LBB0_253
	global_store_dwordx4 v[224:225], v[154:157], off nt
	global_store_dwordx4 v[224:225], v[150:153], off offset:16 nt
.LBB0_253:
	v_cvt_pk_bf16_f32 v242, v154, v155
	v_cvt_pk_bf16_f32 v243, v156, v157
	v_cvt_pk_bf16_f32 v244, v150, v151
	v_cvt_pk_bf16_f32 v245, v152, v153
	v_lshl_add_u64 v[222:223], v[222:223], 1, v[202:203]
	global_store_dwordx4 v[222:223], v[242:245], off nt
	s_and_b64 vcc, exec, s[40:41]
	s_nop 0
	v_lshlrev_b32_e32 v242, 16, v186
	v_and_b32_e32 v243, 0xffff0000, v186
	v_lshlrev_b32_e32 v186, 16, v187
	v_and_b32_e32 v187, 0xffff0000, v187
	v_lshlrev_b32_e32 v244, 16, v188
	v_and_b32_e32 v245, 0xffff0000, v188
	v_lshlrev_b32_e32 v188, 16, v189
	v_and_b32_e32 v189, 0xffff0000, v189
	v_pk_add_f32 v[144:145], v[144:145], v[186:187]
	v_pk_add_f32 v[142:143], v[142:143], v[242:243]
	v_pk_add_f32 v[140:141], v[140:141], v[188:189]
	v_pk_add_f32 v[138:139], v[138:139], v[244:245]
	s_cbranch_vccnz .LBB0_255
	global_store_dwordx4 v[224:225], v[142:145], off offset:512 nt
	global_store_dwordx4 v[224:225], v[138:141], off offset:528 nt
.LBB0_255:
	v_mul_f32_e32 v155, v155, v155
	v_fmac_f32_e32 v155, v154, v154
	v_mul_f32_e32 v154, v157, v157
	v_fmac_f32_e32 v154, v156, v156
	v_mul_f32_e32 v151, v151, v151
	v_add_f32_e32 v154, v155, v154
	v_fmac_f32_e32 v151, v150, v150
	v_add_f32_e32 v150, v151, v154
	v_mul_f32_e32 v151, v153, v153
	v_fmac_f32_e32 v151, v152, v152
	v_add_f32_e32 v150, v151, v150
	v_mul_f32_e32 v151, v143, v143
	v_mul_f32_e32 v152, v145, v145
	v_fmac_f32_e32 v151, v142, v142
	v_fmac_f32_e32 v152, v144, v144
	v_add_f32_e32 v151, v151, v152
	v_mul_f32_e32 v152, v139, v139
	v_fmac_f32_e32 v152, v138, v138
	v_add_f32_e32 v151, v152, v151
	v_mul_f32_e32 v152, v141, v141
	v_fmac_f32_e32 v152, v140, v140
	v_add_f32_e32 v151, v152, v151
	v_add_f32_e32 v150, v150, v151
	v_cvt_pk_bf16_f32 v142, v142, v143
	v_cvt_pk_bf16_f32 v143, v144, v145
	v_cvt_pk_bf16_f32 v144, v138, v139
	v_mov_b32_e32 v138, v150
	s_nop 1
	v_permlane16_swap_b32_e32 v150, v138
	v_cvt_pk_bf16_f32 v145, v140, v141
	v_add_f32_e32 v140, v150, v138
	v_mov_b32_e32 v141, v140
	s_nop 1
	v_permlane32_swap_b32_e32 v140, v141
	v_lshl_add_u64 v[138:139], v[220:221], 3, s[46:47]
	global_store_dwordx4 v[222:223], v[142:145], off offset:256 nt
	s_and_saveexec_b64 s[66:67], s[62:63]
	v_readlane_b32 s96, v250, 17
	v_readlane_b32 s98, v250, 19
	v_readlane_b32 s97, v250, 18
	v_readlane_b32 s99, v250, 20
	s_cbranch_execz .LBB0_257
	v_add_f32_e32 v140, v140, v141
	v_mul_f32_e32 v140, 0x49800000, v140
	v_rndne_f32_e32 v140, v140
	s_mov_b32 s2, 0x2f800000
	v_mul_f32_e64 v141, |v140|, s2
	v_floor_f32_e32 v141, v141
	s_mov_b32 s2, 0xcf800000
	v_fma_f32 v142, v141, s2, |v140|
	v_cvt_u32_f32_e32 v142, v142
	v_cvt_u32_f32_e32 v141, v141
	v_ashrrev_i32_e32 v143, 31, v140
	v_xor_b32_e32 v140, v142, v143
	v_xor_b32_e32 v141, v141, v143
	v_sub_co_u32_e32 v140, vcc, v140, v143
	s_nop 1
	v_subb_co_u32_e32 v141, vcc, v141, v143, vcc
	global_atomic_add_x2 v[138:139], v[140:141], off
; __device__ __forceinline__ unsigned cvt_pk_bf16(float lo, float hi) { unsigned r; asm volatile("v_cvt_pk_bf16_f32 %0, %1, %2" : "=v"(r) : "v"(lo), "v"(hi)); return r; }
; DI float x16_sum(float x) { const unsigned u = __builtin_bit_cast(unsigned, x); auto r = __builtin_amdgcn_permlane16_swap(u, u, false, false); return __builtin_bit_cast(float, (unsigned)r[0]) + __builtin_bit_cast(float, (unsigned)r[1]); }
; DI float x32_sum(float x) { const unsigned u = __builtin_bit_cast(unsigned, x); auto r = __builtin_amdgcn_permlane32_swap(u, u, false, false); return __builtin_bit_cast(float, (unsigned)r[0]) + __builtin_bit_cast(float, (unsigned)r[1]); }
;     __device__ __forceinline__ void operator()(const f32x4 (&acc)[2][2][4][2], const Unit& u, int wr, int wc, int fr, int fq) const {
;     ...
;         for (int ai = 0; ai < 2; ++ai)
; #pragma unroll
;             for (int m = 0; m < 4; ++m) {
;                 const int r = row0 + ai * HALF + m * 16; const size_t off = (size_t)r * 1024 + col0; float s = 0.f;
; #pragma unroll
;                 for (int bj = 0; bj < 2; ++bj) {
;                     const u32x4 bw = pre[ai][m][bj];
;                     f32x4 b0, b1; b0[0] = __builtin_bit_cast(float, bw.x << 16); b0[1] = __builtin_bit_cast(float, bw.x & 0xffff0000u); b0[2] = __builtin_bit_cast(float, bw.y << 16); b0[3] = __builtin_bit_cast(float, bw.y & 0xffff0000u);
;                     b1[0] = __builtin_bit_cast(float, bw.z << 16); b1[1] = __builtin_bit_cast(float, bw.z & 0xffff0000u); b1[2] = __builtin_bit_cast(float, bw.w << 16); b1[3] = __builtin_bit_cast(float, bw.w & 0xffff0000u);
;                     const f32x4 v0 = b0 + acc[ai][bj][m][0], v1 = b1 + acc[ai][bj][m][1];
;                     if (X) { *(f32x4*)(X + off + bj * HALF) = v0; *(f32x4*)(X + off + bj * HALF + 4) = v1; }
;                     s += (v0[0] * v0[0] + v0[1] * v0[1]) + (v0[2] * v0[2] + v0[3] * v0[3]) + (v1[0] * v1[0] + v1[1] * v1[1]) + (v1[2] * v1[2] + v1[3] * v1[3]);
;                     u32x4 w; w.x = cvt_pk_bf16(v0[0], v0[1]); w.y = cvt_pk_bf16(v0[2], v0[3]); w.z = cvt_pk_bf16(v1[0], v1[1]); w.w = cvt_pk_bf16(v1[2], v1[3]);
;                     *(u32x4*)(XB + off + bj * HALF) = w; }
;                 s = x16_sum(s); s = x32_sum(s);
;                 if (fq == 0 && ssn) atomicAdd((unsigned long long*)(ssn + r), (unsigned long long)__float2ll_rn(s * 1048576.0f));
.LBB0_257:
	s_or_b64 exec, exec, s[66:67]
	v_lshlrev_b64 v[140:141], 10, v[218:219]
	v_lshl_add_u64 v[142:143], v[140:141], 0, v[204:205]
	v_lshlrev_b32_e32 v144, 16, v182
	v_and_b32_e32 v145, 0xffff0000, v182
	v_lshlrev_b32_e32 v150, 16, v183
	v_and_b32_e32 v151, 0xffff0000, v183
	v_lshlrev_b32_e32 v152, 16, v184
	v_and_b32_e32 v153, 0xffff0000, v184
	v_lshlrev_b32_e32 v154, 16, v185
	v_and_b32_e32 v155, 0xffff0000, v185
	v_pk_add_f32 v[132:133], v[132:133], v[150:151]
	v_pk_add_f32 v[130:131], v[130:131], v[144:145]
	v_pk_add_f32 v[128:129], v[128:129], v[154:155]
	v_pk_add_f32 v[126:127], v[126:127], v[152:153]
	s_and_b64 vcc, exec, s[40:41]
	v_lshl_add_u64 v[142:143], v[142:143], 2, s[48:49]
	v_readlane_b32 s99, v250, 22
	s_cbranch_vccnz .LBB0_259
	global_store_dwordx4 v[142:143], v[130:133], off nt
	global_store_dwordx4 v[142:143], v[126:129], off offset:16 nt
.LBB0_259:
	v_cvt_pk_bf16_f32 v150, v130, v131
	v_cvt_pk_bf16_f32 v151, v132, v133
	v_cvt_pk_bf16_f32 v152, v126, v127
	v_cvt_pk_bf16_f32 v153, v128, v129
	v_lshl_add_u64 v[140:141], v[140:141], 1, v[202:203]
	global_store_dwordx4 v[140:141], v[150:153], off nt
	v_lshlrev_b32_e32 v144, 16, v178
	v_and_b32_e32 v145, 0xffff0000, v178
	v_lshlrev_b32_e32 v150, 16, v179
	v_and_b32_e32 v151, 0xffff0000, v179
	v_lshlrev_b32_e32 v152, 16, v180
	v_and_b32_e32 v153, 0xffff0000, v180
	v_lshlrev_b32_e32 v154, 16, v181
	v_and_b32_e32 v155, 0xffff0000, v181
	v_pk_add_f32 v[120:121], v[120:121], v[150:151]
	v_pk_add_f32 v[118:119], v[118:119], v[144:145]
	v_pk_add_f32 v[116:117], v[116:117], v[154:155]
	s_and_b64 vcc, exec, s[40:41]
	v_pk_add_f32 v[114:115], v[114:115], v[152:153]
	v_readlane_b32 s97, v250, 21
	s_cbranch_vccnz .LBB0_261
	global_store_dwordx4 v[142:143], v[118:121], off offset:512 nt
	global_store_dwordx4 v[142:143], v[114:117], off offset:528 nt
.LBB0_261:
	v_mul_f32_e32 v131, v131, v131
	v_fmac_f32_e32 v131, v130, v130
	v_mul_f32_e32 v130, v133, v133
	v_fmac_f32_e32 v130, v132, v132
	v_mul_f32_e32 v127, v127, v127
	v_add_f32_e32 v130, v131, v130
	v_fmac_f32_e32 v127, v126, v126
	v_add_f32_e32 v126, v127, v130
	v_mul_f32_e32 v127, v129, v129
	v_fmac_f32_e32 v127, v128, v128
	v_add_f32_e32 v126, v127, v126
	v_mul_f32_e32 v127, v119, v119
	v_mul_f32_e32 v128, v121, v121
	v_fmac_f32_e32 v127, v118, v118
	v_fmac_f32_e32 v128, v120, v120
	v_add_f32_e32 v127, v127, v128
	v_mul_f32_e32 v128, v115, v115
	v_fmac_f32_e32 v128, v114, v114
	v_add_f32_e32 v127, v128, v127
	v_mul_f32_e32 v128, v117, v117
	v_fmac_f32_e32 v128, v116, v116
	v_add_f32_e32 v127, v128, v127
	v_add_f32_e32 v126, v126, v127
	v_cvt_pk_bf16_f32 v118, v118, v119
	v_cvt_pk_bf16_f32 v119, v120, v121
	v_cvt_pk_bf16_f32 v120, v114, v115
	v_mov_b32_e32 v114, v126
	s_nop 1
	v_permlane16_swap_b32_e32 v126, v114
	v_add_f32_e32 v114, v126, v114
	v_mov_b32_e32 v115, v114
	s_nop 1
	v_permlane32_swap_b32_e32 v114, v115
	v_cvt_pk_bf16_f32 v121, v116, v117
	global_store_dwordx4 v[140:141], v[118:121], off offset:256 nt
	s_and_saveexec_b64 s[66:67], s[62:63]
	s_cbranch_execz .LBB0_263
	v_add_f32_e32 v114, v114, v115
	v_mul_f32_e32 v114, 0x49800000, v114
	v_rndne_f32_e32 v114, v114
	s_mov_b32 s2, 0x2f800000
	v_mul_f32_e64 v115, |v114|, s2
	v_floor_f32_e32 v115, v115
	s_mov_b32 s2, 0xcf800000
	v_fma_f32 v116, v115, s2, |v114|
	v_cvt_u32_f32_e32 v116, v116
	v_cvt_u32_f32_e32 v115, v115
	v_ashrrev_i32_e32 v117, 31, v114
	v_xor_b32_e32 v114, v116, v117
	v_xor_b32_e32 v115, v115, v117
	v_sub_co_u32_e32 v114, vcc, v114, v117
	s_nop 1
	v_subb_co_u32_e32 v115, vcc, v115, v117, vcc
	global_atomic_add_x2 v[138:139], v[114:115], off offset:128
.LBB0_263:
	s_or_b64 exec, exec, s[66:67]
	v_lshlrev_b64 v[114:115], 10, v[216:217]
	v_lshl_add_u64 v[116:117], v[114:115], 0, v[204:205]
	v_lshlrev_b32_e32 v118, 16, v174
	v_and_b32_e32 v119, 0xffff0000, v174
	v_lshlrev_b32_e32 v120, 16, v175
	v_and_b32_e32 v121, 0xffff0000, v175
	v_lshlrev_b32_e32 v126, 16, v176
	v_and_b32_e32 v127, 0xffff0000, v176
	v_lshlrev_b32_e32 v128, 16, v177
	v_and_b32_e32 v129, 0xffff0000, v177
	v_pk_add_f32 v[106:107], v[106:107], v[120:121]
	v_pk_add_f32 v[104:105], v[104:105], v[118:119]
	v_pk_add_f32 v[98:99], v[98:99], v[128:129]
	v_pk_add_f32 v[96:97], v[96:97], v[126:127]
	s_and_b64 vcc, exec, s[40:41]
	v_lshl_add_u64 v[116:117], v[116:117], 2, s[48:49]
	s_cbranch_vccnz .LBB0_265
	global_store_dwordx4 v[116:117], v[104:107], off nt
	global_store_dwordx4 v[116:117], v[96:99], off offset:16 nt
.LBB0_265:
	v_cvt_pk_bf16_f32 v118, v104, v105
	v_cvt_pk_bf16_f32 v119, v106, v107
	v_cvt_pk_bf16_f32 v120, v96, v97
	v_cvt_pk_bf16_f32 v121, v98, v99
	v_lshl_add_u64 v[114:115], v[114:115], 1, v[202:203]
	global_store_dwordx4 v[114:115], v[118:121], off nt
	v_lshlrev_b32_e32 v126, 16, v172
	v_and_b32_e32 v127, 0xffff0000, v172
	v_lshlrev_b32_e32 v118, 16, v170
	v_and_b32_e32 v119, 0xffff0000, v170
	v_lshlrev_b32_e32 v120, 16, v171
	v_and_b32_e32 v121, 0xffff0000, v171
	v_lshlrev_b32_e32 v128, 16, v173
	v_and_b32_e32 v129, 0xffff0000, v173
	v_pk_add_f32 v[94:95], v[94:95], v[120:121]
	v_pk_add_f32 v[92:93], v[92:93], v[118:119]
	v_pk_add_f32 v[90:91], v[90:91], v[128:129]
	s_and_b64 vcc, exec, s[40:41]
	v_pk_add_f32 v[88:89], v[88:89], v[126:127]
	s_cbranch_vccnz .LBB0_267
	global_store_dwordx4 v[116:117], v[92:95], off offset:512 nt
	global_store_dwordx4 v[116:117], v[88:91], off offset:528 nt
; __device__ __forceinline__ unsigned cvt_pk_bf16(float lo, float hi) { unsigned r; asm volatile("v_cvt_pk_bf16_f32 %0, %1, %2" : "=v"(r) : "v"(lo), "v"(hi)); return r; }
; DI float x16_sum(float x) { const unsigned u = __builtin_bit_cast(unsigned, x); auto r = __builtin_amdgcn_permlane16_swap(u, u, false, false); return __builtin_bit_cast(float, (unsigned)r[0]) + __builtin_bit_cast(float, (unsigned)r[1]); }
; DI float x32_sum(float x) { const unsigned u = __builtin_bit_cast(unsigned, x); auto r = __builtin_amdgcn_permlane32_swap(u, u, false, false); return __builtin_bit_cast(float, (unsigned)r[0]) + __builtin_bit_cast(float, (unsigned)r[1]); }
;     __device__ __forceinline__ void operator()(const f32x4 (&acc)[2][2][4][2], const Unit& u, int wr, int wc, int fr, int fq) const {
;     ...
;         for (int ai = 0; ai < 2; ++ai)
; #pragma unroll
;             for (int m = 0; m < 4; ++m) {
;                 const int r = row0 + ai * HALF + m * 16; const size_t off = (size_t)r * 1024 + col0; float s = 0.f;
; #pragma unroll
;                 for (int bj = 0; bj < 2; ++bj) {
;                     const u32x4 bw = pre[ai][m][bj];
;                     f32x4 b0, b1; b0[0] = __builtin_bit_cast(float, bw.x << 16); b0[1] = __builtin_bit_cast(float, bw.x & 0xffff0000u); b0[2] = __builtin_bit_cast(float, bw.y << 16); b0[3] = __builtin_bit_cast(float, bw.y & 0xffff0000u);
;                     b1[0] = __builtin_bit_cast(float, bw.z << 16); b1[1] = __builtin_bit_cast(float, bw.z & 0xffff0000u); b1[2] = __builtin_bit_cast(float, bw.w << 16); b1[3] = __builtin_bit_cast(float, bw.w & 0xffff0000u);
;                     const f32x4 v0 = b0 + acc[ai][bj][m][0], v1 = b1 + acc[ai][bj][m][1];
;                     if (X) { *(f32x4*)(X + off + bj * HALF) = v0; *(f32x4*)(X + off + bj * HALF + 4) = v1; }
;                     s += (v0[0] * v0[0] + v0[1] * v0[1]) + (v0[2] * v0[2] + v0[3] * v0[3]) + (v1[0] * v1[0] + v1[1] * v1[1]) + (v1[2] * v1[2] + v1[3] * v1[3]);
;                     u32x4 w; w.x = cvt_pk_bf16(v0[0], v0[1]); w.y = cvt_pk_bf16(v0[2], v0[3]); w.z = cvt_pk_bf16(v1[0], v1[1]); w.w = cvt_pk_bf16(v1[2], v1[3]);
;                     *(u32x4*)(XB + off + bj * HALF) = w; }
;                 s = x16_sum(s); s = x32_sum(s);
;                 if (fq == 0 && ssn) atomicAdd((unsigned long long*)(ssn + r), (unsigned long long)__float2ll_rn(s * 1048576.0f));
.LBB0_267:
	v_mul_f32_e32 v105, v105, v105
	v_fmac_f32_e32 v105, v104, v104
	v_mul_f32_e32 v104, v107, v107
	v_fmac_f32_e32 v104, v106, v106
	v_mul_f32_e32 v97, v97, v97
	v_add_f32_e32 v104, v105, v104
	v_fmac_f32_e32 v97, v96, v96
	v_add_f32_e32 v96, v97, v104
	v_mul_f32_e32 v97, v99, v99
	v_fmac_f32_e32 v97, v98, v98
	v_add_f32_e32 v96, v97, v96
	v_mul_f32_e32 v97, v93, v93
	v_mul_f32_e32 v98, v95, v95
	v_fmac_f32_e32 v97, v92, v92
	v_fmac_f32_e32 v98, v94, v94
	v_add_f32_e32 v97, v97, v98
	v_mul_f32_e32 v98, v89, v89
	v_fmac_f32_e32 v98, v88, v88
	v_add_f32_e32 v97, v98, v97
	v_mul_f32_e32 v98, v91, v91
	v_fmac_f32_e32 v98, v90, v90
	v_add_f32_e32 v97, v98, v97
	v_add_f32_e32 v96, v96, v97
	v_cvt_pk_bf16_f32 v92, v92, v93
	v_cvt_pk_bf16_f32 v93, v94, v95
	v_cvt_pk_bf16_f32 v94, v88, v89
	v_mov_b32_e32 v88, v96
	s_nop 1
	v_permlane16_swap_b32_e32 v96, v88
	v_add_f32_e32 v88, v96, v88
	v_mov_b32_e32 v89, v88
	s_nop 1
	v_permlane32_swap_b32_e32 v88, v89
	v_cvt_pk_bf16_f32 v95, v90, v91
	global_store_dwordx4 v[114:115], v[92:95], off offset:256 nt
	s_and_saveexec_b64 s[66:67], s[62:63]
	s_cbranch_execz .LBB0_269
	v_add_f32_e32 v88, v88, v89
	v_mul_f32_e32 v88, 0x49800000, v88
	v_rndne_f32_e32 v88, v88
	s_mov_b32 s2, 0x2f800000
	v_mul_f32_e64 v89, |v88|, s2
	v_floor_f32_e32 v89, v89
	s_mov_b32 s2, 0xcf800000
	v_fma_f32 v90, v89, s2, |v88|
	v_cvt_u32_f32_e32 v90, v90
	v_cvt_u32_f32_e32 v89, v89
	v_ashrrev_i32_e32 v91, 31, v88
	v_xor_b32_e32 v88, v90, v91
	v_xor_b32_e32 v89, v89, v91
	v_sub_co_u32_e32 v88, vcc, v88, v91
	s_nop 1
	v_subb_co_u32_e32 v89, vcc, v89, v91, vcc
	global_atomic_add_x2 v[138:139], v[88:89], off offset:256
.LBB0_269:
	s_or_b64 exec, exec, s[66:67]
	v_lshlrev_b64 v[88:89], 10, v[214:215]
	v_lshl_add_u64 v[90:91], v[88:89], 0, v[204:205]
	v_lshlrev_b32_e32 v92, 16, v166
	v_and_b32_e32 v93, 0xffff0000, v166
	v_lshlrev_b32_e32 v94, 16, v167
	v_and_b32_e32 v95, 0xffff0000, v167
	v_lshlrev_b32_e32 v96, 16, v168
	v_and_b32_e32 v97, 0xffff0000, v168
	v_lshlrev_b32_e32 v98, 16, v169
	v_and_b32_e32 v99, 0xffff0000, v169
	v_pk_add_f32 v[78:79], v[78:79], v[94:95]
	v_pk_add_f32 v[76:77], v[76:77], v[92:93]
	v_pk_add_f32 v[74:75], v[74:75], v[98:99]
	v_pk_add_f32 v[72:73], v[72:73], v[96:97]
	s_and_b64 vcc, exec, s[40:41]
	v_lshl_add_u64 v[90:91], v[90:91], 2, s[48:49]
	s_cbranch_vccnz .LBB0_271
	global_store_dwordx4 v[90:91], v[76:79], off nt
	global_store_dwordx4 v[90:91], v[72:75], off offset:16 nt
.LBB0_271:
	v_cvt_pk_bf16_f32 v92, v76, v77
	v_cvt_pk_bf16_f32 v93, v78, v79
	v_cvt_pk_bf16_f32 v94, v72, v73
	v_cvt_pk_bf16_f32 v95, v74, v75
	v_lshl_add_u64 v[88:89], v[88:89], 1, v[202:203]
	global_store_dwordx4 v[88:89], v[92:95], off nt
	v_lshlrev_b32_e32 v96, 16, v164
	v_and_b32_e32 v97, 0xffff0000, v164
	v_lshlrev_b32_e32 v92, 16, v162
	v_and_b32_e32 v93, 0xffff0000, v162
	v_lshlrev_b32_e32 v94, 16, v163
	v_and_b32_e32 v95, 0xffff0000, v163
	v_lshlrev_b32_e32 v98, 16, v165
	v_and_b32_e32 v99, 0xffff0000, v165
	v_pk_add_f32 v[70:71], v[70:71], v[94:95]
	v_pk_add_f32 v[68:69], v[68:69], v[92:93]
	v_pk_add_f32 v[66:67], v[66:67], v[98:99]
	s_and_b64 vcc, exec, s[40:41]
	v_pk_add_f32 v[64:65], v[64:65], v[96:97]
	s_cbranch_vccnz .LBB0_273
	global_store_dwordx4 v[90:91], v[68:71], off offset:512 nt
	global_store_dwordx4 v[90:91], v[64:67], off offset:528 nt
.LBB0_273:
	v_mul_f32_e32 v77, v77, v77
	v_fmac_f32_e32 v77, v76, v76
	v_mul_f32_e32 v76, v79, v79
	v_fmac_f32_e32 v76, v78, v78
	v_mul_f32_e32 v73, v73, v73
	v_add_f32_e32 v76, v77, v76
	v_fmac_f32_e32 v73, v72, v72
	v_add_f32_e32 v72, v73, v76
	v_mul_f32_e32 v73, v75, v75
	v_fmac_f32_e32 v73, v74, v74
	v_add_f32_e32 v72, v73, v72
	v_mul_f32_e32 v73, v69, v69
	v_mul_f32_e32 v74, v71, v71
	v_fmac_f32_e32 v73, v68, v68
	v_fmac_f32_e32 v74, v70, v70
	v_add_f32_e32 v73, v73, v74
	v_mul_f32_e32 v74, v65, v65
	v_fmac_f32_e32 v74, v64, v64
	v_add_f32_e32 v73, v74, v73
	v_mul_f32_e32 v74, v67, v67
	v_fmac_f32_e32 v74, v66, v66
	v_add_f32_e32 v73, v74, v73
	v_add_f32_e32 v72, v72, v73
	v_cvt_pk_bf16_f32 v68, v68, v69
	v_cvt_pk_bf16_f32 v69, v70, v71
	v_cvt_pk_bf16_f32 v70, v64, v65
	v_mov_b32_e32 v64, v72
	s_nop 1
	v_permlane16_swap_b32_e32 v72, v64
	v_add_f32_e32 v64, v72, v64
	v_mov_b32_e32 v65, v64
	s_nop 1
	v_permlane32_swap_b32_e32 v64, v65
	v_cvt_pk_bf16_f32 v71, v66, v67
	global_store_dwordx4 v[88:89], v[68:71], off offset:256 nt
	s_and_saveexec_b64 s[66:67], s[62:63]
	s_cbranch_execz .LBB0_275
	v_add_f32_e32 v64, v64, v65
	v_mul_f32_e32 v64, 0x49800000, v64
	v_rndne_f32_e32 v64, v64
	s_mov_b32 s2, 0x2f800000
	v_mul_f32_e64 v65, |v64|, s2
	v_floor_f32_e32 v65, v65
	s_mov_b32 s2, 0xcf800000
	v_fma_f32 v66, v65, s2, |v64|
	v_cvt_u32_f32_e32 v66, v66
	v_cvt_u32_f32_e32 v65, v65
	v_ashrrev_i32_e32 v67, 31, v64
	v_xor_b32_e32 v64, v66, v67
	v_xor_b32_e32 v65, v65, v67
	v_sub_co_u32_e32 v64, vcc, v64, v67
	s_nop 1
	v_subb_co_u32_e32 v65, vcc, v65, v67, vcc
	global_atomic_add_x2 v[138:139], v[64:65], off offset:384
.LBB0_275:
	s_or_b64 exec, exec, s[66:67]
	v_lshlrev_b64 v[64:65], 10, v[212:213]
	v_lshl_add_u64 v[66:67], v[64:65], 0, v[204:205]
	v_lshlrev_b32_e32 v68, 16, v158
	v_and_b32_e32 v69, 0xffff0000, v158
	v_lshlrev_b32_e32 v70, 16, v159
	v_and_b32_e32 v71, 0xffff0000, v159
	v_lshlrev_b32_e32 v72, 16, v160
	v_and_b32_e32 v73, 0xffff0000, v160
	v_lshlrev_b32_e32 v74, 16, v161
	v_and_b32_e32 v75, 0xffff0000, v161
	v_pk_add_f32 v[62:63], v[62:63], v[70:71]
	v_pk_add_f32 v[60:61], v[60:61], v[68:69]
	v_pk_add_f32 v[58:59], v[58:59], v[74:75]
	v_pk_add_f32 v[56:57], v[56:57], v[72:73]
	s_and_b64 vcc, exec, s[40:41]
	v_lshl_add_u64 v[66:67], v[66:67], 2, s[48:49]
	s_cbranch_vccnz .LBB0_277
	global_store_dwordx4 v[66:67], v[60:63], off nt
	global_store_dwordx4 v[66:67], v[56:59], off offset:16 nt
; __device__ __forceinline__ unsigned cvt_pk_bf16(float lo, float hi) { unsigned r; asm volatile("v_cvt_pk_bf16_f32 %0, %1, %2" : "=v"(r) : "v"(lo), "v"(hi)); return r; }
; DI float x16_sum(float x) { const unsigned u = __builtin_bit_cast(unsigned, x); auto r = __builtin_amdgcn_permlane16_swap(u, u, false, false); return __builtin_bit_cast(float, (unsigned)r[0]) + __builtin_bit_cast(float, (unsigned)r[1]); }
; DI float x32_sum(float x) { const unsigned u = __builtin_bit_cast(unsigned, x); auto r = __builtin_amdgcn_permlane32_swap(u, u, false, false); return __builtin_bit_cast(float, (unsigned)r[0]) + __builtin_bit_cast(float, (unsigned)r[1]); }
;     __device__ __forceinline__ void operator()(const f32x4 (&acc)[2][2][4][2], const Unit& u, int wr, int wc, int fr, int fq) const {
;     ...
;         for (int ai = 0; ai < 2; ++ai)
; #pragma unroll
;             for (int m = 0; m < 4; ++m) {
;                 const int r = row0 + ai * HALF + m * 16; const size_t off = (size_t)r * 1024 + col0; float s = 0.f;
; #pragma unroll
;                 for (int bj = 0; bj < 2; ++bj) {
;                     const u32x4 bw = pre[ai][m][bj];
;                     f32x4 b0, b1; b0[0] = __builtin_bit_cast(float, bw.x << 16); b0[1] = __builtin_bit_cast(float, bw.x & 0xffff0000u); b0[2] = __builtin_bit_cast(float, bw.y << 16); b0[3] = __builtin_bit_cast(float, bw.y & 0xffff0000u);
;                     b1[0] = __builtin_bit_cast(float, bw.z << 16); b1[1] = __builtin_bit_cast(float, bw.z & 0xffff0000u); b1[2] = __builtin_bit_cast(float, bw.w << 16); b1[3] = __builtin_bit_cast(float, bw.w & 0xffff0000u);
;                     const f32x4 v0 = b0 + acc[ai][bj][m][0], v1 = b1 + acc[ai][bj][m][1];
;                     if (X) { *(f32x4*)(X + off + bj * HALF) = v0; *(f32x4*)(X + off + bj * HALF + 4) = v1; }
;                     s += (v0[0] * v0[0] + v0[1] * v0[1]) + (v0[2] * v0[2] + v0[3] * v0[3]) + (v1[0] * v1[0] + v1[1] * v1[1]) + (v1[2] * v1[2] + v1[3] * v1[3]);
;                     u32x4 w; w.x = cvt_pk_bf16(v0[0], v0[1]); w.y = cvt_pk_bf16(v0[2], v0[3]); w.z = cvt_pk_bf16(v1[0], v1[1]); w.w = cvt_pk_bf16(v1[2], v1[3]);
;                     *(u32x4*)(XB + off + bj * HALF) = w; }
;                 s = x16_sum(s); s = x32_sum(s);
;                 if (fq == 0 && ssn) atomicAdd((unsigned long long*)(ssn + r), (unsigned long long)__float2ll_rn(s * 1048576.0f));
.LBB0_277:
	v_cvt_pk_bf16_f32 v68, v60, v61
	v_cvt_pk_bf16_f32 v69, v62, v63
	v_cvt_pk_bf16_f32 v70, v56, v57
	v_cvt_pk_bf16_f32 v71, v58, v59
	v_lshl_add_u64 v[64:65], v[64:65], 1, v[202:203]
	global_store_dwordx4 v[64:65], v[68:71], off nt
	v_lshlrev_b32_e32 v72, 16, v148
	v_and_b32_e32 v73, 0xffff0000, v148
	v_lshlrev_b32_e32 v68, 16, v146
	v_and_b32_e32 v69, 0xffff0000, v146
	v_lshlrev_b32_e32 v70, 16, v147
	v_and_b32_e32 v71, 0xffff0000, v147
	v_lshlrev_b32_e32 v74, 16, v149
	v_and_b32_e32 v75, 0xffff0000, v149
	v_pk_add_f32 v[54:55], v[54:55], v[70:71]
	v_pk_add_f32 v[52:53], v[52:53], v[68:69]
	v_pk_add_f32 v[50:51], v[50:51], v[74:75]
	s_and_b64 vcc, exec, s[40:41]
	v_pk_add_f32 v[48:49], v[48:49], v[72:73]
	s_cbranch_vccnz .LBB0_279
	global_store_dwordx4 v[66:67], v[52:55], off offset:512 nt
	global_store_dwordx4 v[66:67], v[48:51], off offset:528 nt
.LBB0_279:
	v_mul_f32_e32 v61, v61, v61
	v_fmac_f32_e32 v61, v60, v60
	v_mul_f32_e32 v60, v63, v63
	v_fmac_f32_e32 v60, v62, v62
	v_mul_f32_e32 v57, v57, v57
	v_add_f32_e32 v60, v61, v60
	v_fmac_f32_e32 v57, v56, v56
	v_add_f32_e32 v56, v57, v60
	v_mul_f32_e32 v57, v59, v59
	v_fmac_f32_e32 v57, v58, v58
	v_add_f32_e32 v56, v57, v56
	v_mul_f32_e32 v57, v53, v53
	v_mul_f32_e32 v58, v55, v55
	v_fmac_f32_e32 v57, v52, v52
	v_fmac_f32_e32 v58, v54, v54
	v_add_f32_e32 v57, v57, v58
	v_mul_f32_e32 v58, v49, v49
	v_fmac_f32_e32 v58, v48, v48
	v_add_f32_e32 v57, v58, v57
	v_mul_f32_e32 v58, v51, v51
	v_fmac_f32_e32 v58, v50, v50
	v_add_f32_e32 v57, v58, v57
	v_add_f32_e32 v56, v56, v57
	v_cvt_pk_bf16_f32 v52, v52, v53
	v_cvt_pk_bf16_f32 v53, v54, v55
	v_cvt_pk_bf16_f32 v54, v48, v49
	v_mov_b32_e32 v48, v56
	s_nop 1
	v_permlane16_swap_b32_e32 v56, v48
	v_add_f32_e32 v48, v56, v48
	v_mov_b32_e32 v49, v48
	s_nop 1
	v_permlane32_swap_b32_e32 v48, v49
	v_cvt_pk_bf16_f32 v55, v50, v51
	global_store_dwordx4 v[64:65], v[52:55], off offset:256 nt
	s_and_saveexec_b64 s[66:67], s[62:63]
	s_cbranch_execz .LBB0_281
	v_add_f32_e32 v48, v48, v49
	v_mul_f32_e32 v48, 0x49800000, v48
	v_rndne_f32_e32 v48, v48
	s_mov_b32 s2, 0x2f800000
	v_mul_f32_e64 v49, |v48|, s2
	v_floor_f32_e32 v49, v49
	s_mov_b32 s2, 0xcf800000
	v_fma_f32 v50, v49, s2, |v48|
	v_cvt_u32_f32_e32 v50, v50
	v_cvt_u32_f32_e32 v49, v49
	v_ashrrev_i32_e32 v51, 31, v48
	v_xor_b32_e32 v48, v50, v51
	v_xor_b32_e32 v49, v49, v51
	v_sub_co_u32_e32 v48, vcc, v48, v51
	s_nop 1
	v_subb_co_u32_e32 v49, vcc, v49, v51, vcc
	global_atomic_add_x2 v[138:139], v[48:49], off offset:1024
.LBB0_281:
	s_or_b64 exec, exec, s[66:67]
	v_lshlrev_b64 v[48:49], 10, v[210:211]
	v_lshl_add_u64 v[50:51], v[48:49], 0, v[204:205]
	v_lshlrev_b32_e32 v52, 16, v134
	v_and_b32_e32 v53, 0xffff0000, v134
	v_lshlrev_b32_e32 v54, 16, v135
	v_and_b32_e32 v55, 0xffff0000, v135
	v_lshlrev_b32_e32 v56, 16, v136
	v_and_b32_e32 v57, 0xffff0000, v136
	v_lshlrev_b32_e32 v58, 16, v137
	v_and_b32_e32 v59, 0xffff0000, v137
	v_pk_add_f32 v[46:47], v[46:47], v[54:55]
	v_pk_add_f32 v[44:45], v[44:45], v[52:53]
	v_pk_add_f32 v[42:43], v[42:43], v[58:59]
	v_pk_add_f32 v[40:41], v[40:41], v[56:57]
	s_and_b64 vcc, exec, s[40:41]
	v_lshl_add_u64 v[50:51], v[50:51], 2, s[48:49]
	s_cbranch_vccnz .LBB0_283
	global_store_dwordx4 v[50:51], v[44:47], off nt
	global_store_dwordx4 v[50:51], v[40:43], off offset:16 nt
.LBB0_283:
	v_cvt_pk_bf16_f32 v52, v44, v45
	v_cvt_pk_bf16_f32 v53, v46, v47
	v_cvt_pk_bf16_f32 v54, v40, v41
	v_cvt_pk_bf16_f32 v55, v42, v43
	v_lshl_add_u64 v[48:49], v[48:49], 1, v[202:203]
	global_store_dwordx4 v[48:49], v[52:55], off nt
	v_lshlrev_b32_e32 v56, 16, v124
	v_and_b32_e32 v57, 0xffff0000, v124
	v_lshlrev_b32_e32 v52, 16, v122
	v_and_b32_e32 v53, 0xffff0000, v122
	v_lshlrev_b32_e32 v54, 16, v123
	v_and_b32_e32 v55, 0xffff0000, v123
	v_lshlrev_b32_e32 v58, 16, v125
	v_and_b32_e32 v59, 0xffff0000, v125
	v_pk_add_f32 v[38:39], v[38:39], v[54:55]
	v_pk_add_f32 v[36:37], v[36:37], v[52:53]
	v_pk_add_f32 v[34:35], v[34:35], v[58:59]
	s_and_b64 vcc, exec, s[40:41]
	v_pk_add_f32 v[32:33], v[32:33], v[56:57]
	s_cbranch_vccnz .LBB0_285
	global_store_dwordx4 v[50:51], v[36:39], off offset:512 nt
	global_store_dwordx4 v[50:51], v[32:35], off offset:528 nt
.LBB0_285:
	v_mul_f32_e32 v45, v45, v45
	v_fmac_f32_e32 v45, v44, v44
	v_mul_f32_e32 v44, v47, v47
	v_fmac_f32_e32 v44, v46, v46
	v_mul_f32_e32 v41, v41, v41
	v_add_f32_e32 v44, v45, v44
	v_fmac_f32_e32 v41, v40, v40
	v_add_f32_e32 v40, v41, v44
	v_mul_f32_e32 v41, v43, v43
	v_fmac_f32_e32 v41, v42, v42
	v_add_f32_e32 v40, v41, v40
	v_mul_f32_e32 v41, v37, v37
	v_mul_f32_e32 v42, v39, v39
	v_fmac_f32_e32 v41, v36, v36
	v_fmac_f32_e32 v42, v38, v38
	v_add_f32_e32 v41, v41, v42
	v_mul_f32_e32 v42, v33, v33
	v_fmac_f32_e32 v42, v32, v32
	v_add_f32_e32 v41, v42, v41
	v_mul_f32_e32 v42, v35, v35
	v_fmac_f32_e32 v42, v34, v34
	v_add_f32_e32 v41, v42, v41
	v_add_f32_e32 v40, v40, v41
	v_cvt_pk_bf16_f32 v36, v36, v37
	v_cvt_pk_bf16_f32 v37, v38, v39
	v_cvt_pk_bf16_f32 v38, v32, v33
	v_mov_b32_e32 v32, v40
	s_nop 1
	v_permlane16_swap_b32_e32 v40, v32
	v_add_f32_e32 v32, v40, v32
	v_mov_b32_e32 v33, v32
	s_nop 1
	v_permlane32_swap_b32_e32 v32, v33
	v_cvt_pk_bf16_f32 v39, v34, v35
	global_store_dwordx4 v[48:49], v[36:39], off offset:256 nt
	s_and_saveexec_b64 s[66:67], s[62:63]
	s_cbranch_execz .LBB0_287
	v_add_f32_e32 v32, v32, v33
	v_mul_f32_e32 v32, 0x49800000, v32
	v_rndne_f32_e32 v32, v32
	s_mov_b32 s2, 0x2f800000
	v_mul_f32_e64 v33, |v32|, s2
	v_floor_f32_e32 v33, v33
	s_mov_b32 s2, 0xcf800000
	v_fma_f32 v34, v33, s2, |v32|
	v_cvt_u32_f32_e32 v34, v34
	v_cvt_u32_f32_e32 v33, v33
	v_ashrrev_i32_e32 v35, 31, v32
	v_xor_b32_e32 v32, v34, v35
	v_xor_b32_e32 v33, v33, v35
	v_sub_co_u32_e32 v32, vcc, v32, v35
	s_nop 1
	v_subb_co_u32_e32 v33, vcc, v33, v35, vcc
	global_atomic_add_x2 v[138:139], v[32:33], off offset:1152
; __device__ __forceinline__ unsigned cvt_pk_bf16(float lo, float hi) { unsigned r; asm volatile("v_cvt_pk_bf16_f32 %0, %1, %2" : "=v"(r) : "v"(lo), "v"(hi)); return r; }
; DI float x16_sum(float x) { const unsigned u = __builtin_bit_cast(unsigned, x); auto r = __builtin_amdgcn_permlane16_swap(u, u, false, false); return __builtin_bit_cast(float, (unsigned)r[0]) + __builtin_bit_cast(float, (unsigned)r[1]); }
; DI float x32_sum(float x) { const unsigned u = __builtin_bit_cast(unsigned, x); auto r = __builtin_amdgcn_permlane32_swap(u, u, false, false); return __builtin_bit_cast(float, (unsigned)r[0]) + __builtin_bit_cast(float, (unsigned)r[1]); }
;     __device__ __forceinline__ void operator()(const f32x4 (&acc)[2][2][4][2], const Unit& u, int wr, int wc, int fr, int fq) const {
;     ...
;         for (int ai = 0; ai < 2; ++ai)
; #pragma unroll
;             for (int m = 0; m < 4; ++m) {
;                 const int r = row0 + ai * HALF + m * 16; const size_t off = (size_t)r * 1024 + col0; float s = 0.f;
; #pragma unroll
;                 for (int bj = 0; bj < 2; ++bj) {
;                     const u32x4 bw = pre[ai][m][bj];
;                     f32x4 b0, b1; b0[0] = __builtin_bit_cast(float, bw.x << 16); b0[1] = __builtin_bit_cast(float, bw.x & 0xffff0000u); b0[2] = __builtin_bit_cast(float, bw.y << 16); b0[3] = __builtin_bit_cast(float, bw.y & 0xffff0000u);
;                     b1[0] = __builtin_bit_cast(float, bw.z << 16); b1[1] = __builtin_bit_cast(float, bw.z & 0xffff0000u); b1[2] = __builtin_bit_cast(float, bw.w << 16); b1[3] = __builtin_bit_cast(float, bw.w & 0xffff0000u);
;                     const f32x4 v0 = b0 + acc[ai][bj][m][0], v1 = b1 + acc[ai][bj][m][1];
;                     if (X) { *(f32x4*)(X + off + bj * HALF) = v0; *(f32x4*)(X + off + bj * HALF + 4) = v1; }
;                     s += (v0[0] * v0[0] + v0[1] * v0[1]) + (v0[2] * v0[2] + v0[3] * v0[3]) + (v1[0] * v1[0] + v1[1] * v1[1]) + (v1[2] * v1[2] + v1[3] * v1[3]);
;                     u32x4 w; w.x = cvt_pk_bf16(v0[0], v0[1]); w.y = cvt_pk_bf16(v0[2], v0[3]); w.z = cvt_pk_bf16(v1[0], v1[1]); w.w = cvt_pk_bf16(v1[2], v1[3]);
;                     *(u32x4*)(XB + off + bj * HALF) = w; }
;                 s = x16_sum(s); s = x32_sum(s);
;                 if (fq == 0 && ssn) atomicAdd((unsigned long long*)(ssn + r), (unsigned long long)__float2ll_rn(s * 1048576.0f));
.LBB0_287:
	s_or_b64 exec, exec, s[66:67]
	v_lshlrev_b64 v[32:33], 10, v[208:209]
	v_lshl_add_u64 v[34:35], v[32:33], 0, v[204:205]
	v_lshlrev_b32_e32 v36, 16, v108
	v_and_b32_e32 v37, 0xffff0000, v108
	v_lshlrev_b32_e32 v38, 16, v109
	v_and_b32_e32 v39, 0xffff0000, v109
	v_lshlrev_b32_e32 v40, 16, v110
	v_and_b32_e32 v41, 0xffff0000, v110
	v_lshlrev_b32_e32 v42, 16, v111
	v_and_b32_e32 v43, 0xffff0000, v111
	v_pk_add_f32 v[30:31], v[30:31], v[38:39]
	v_pk_add_f32 v[28:29], v[28:29], v[36:37]
	v_pk_add_f32 v[26:27], v[26:27], v[42:43]
	v_pk_add_f32 v[24:25], v[24:25], v[40:41]
	s_and_b64 vcc, exec, s[40:41]
	v_lshl_add_u64 v[34:35], v[34:35], 2, s[48:49]
	s_cbranch_vccnz .LBB0_289
	global_store_dwordx4 v[34:35], v[28:31], off nt
	global_store_dwordx4 v[34:35], v[24:27], off offset:16 nt
.LBB0_289:
	v_cvt_pk_bf16_f32 v36, v28, v29
	v_cvt_pk_bf16_f32 v37, v30, v31
	v_cvt_pk_bf16_f32 v38, v24, v25
	v_cvt_pk_bf16_f32 v39, v26, v27
	v_lshl_add_u64 v[32:33], v[32:33], 1, v[202:203]
	global_store_dwordx4 v[32:33], v[36:39], off nt
	v_lshlrev_b32_e32 v40, 16, v102
	v_and_b32_e32 v41, 0xffff0000, v102
	v_lshlrev_b32_e32 v36, 16, v100
	v_and_b32_e32 v37, 0xffff0000, v100
	v_lshlrev_b32_e32 v38, 16, v101
	v_and_b32_e32 v39, 0xffff0000, v101
	v_lshlrev_b32_e32 v42, 16, v103
	v_and_b32_e32 v43, 0xffff0000, v103
	v_pk_add_f32 v[22:23], v[22:23], v[38:39]
	v_pk_add_f32 v[20:21], v[20:21], v[36:37]
	v_pk_add_f32 v[18:19], v[18:19], v[42:43]
	s_and_b64 vcc, exec, s[40:41]
	v_pk_add_f32 v[16:17], v[16:17], v[40:41]
	s_cbranch_vccnz .LBB0_291
	global_store_dwordx4 v[34:35], v[20:23], off offset:512 nt
	global_store_dwordx4 v[34:35], v[16:19], off offset:528 nt
.LBB0_291:
	v_mul_f32_e32 v29, v29, v29
	v_fmac_f32_e32 v29, v28, v28
	v_mul_f32_e32 v28, v31, v31
	v_fmac_f32_e32 v28, v30, v30
	v_mul_f32_e32 v25, v25, v25
	v_add_f32_e32 v28, v29, v28
	v_fmac_f32_e32 v25, v24, v24
	v_add_f32_e32 v24, v25, v28
	v_mul_f32_e32 v25, v27, v27
	v_fmac_f32_e32 v25, v26, v26
	v_add_f32_e32 v24, v25, v24
	v_mul_f32_e32 v25, v21, v21
	v_mul_f32_e32 v26, v23, v23
	v_fmac_f32_e32 v25, v20, v20
	v_fmac_f32_e32 v26, v22, v22
	v_add_f32_e32 v25, v25, v26
	v_mul_f32_e32 v26, v17, v17
	v_fmac_f32_e32 v26, v16, v16
	v_add_f32_e32 v25, v26, v25
	v_mul_f32_e32 v26, v19, v19
	v_fmac_f32_e32 v26, v18, v18
	v_add_f32_e32 v25, v26, v25
	v_add_f32_e32 v24, v24, v25
	v_cvt_pk_bf16_f32 v20, v20, v21
	v_cvt_pk_bf16_f32 v21, v22, v23
	v_cvt_pk_bf16_f32 v22, v16, v17
	v_mov_b32_e32 v16, v24
	s_nop 1
	v_permlane16_swap_b32_e32 v24, v16
	v_add_f32_e32 v16, v24, v16
	v_mov_b32_e32 v17, v16
	s_nop 1
	v_permlane32_swap_b32_e32 v16, v17
	v_cvt_pk_bf16_f32 v23, v18, v19
	global_store_dwordx4 v[32:33], v[20:23], off offset:256 nt
	s_and_saveexec_b64 s[66:67], s[62:63]
	s_cbranch_execz .LBB0_293
	v_add_f32_e32 v16, v16, v17
	v_mul_f32_e32 v16, 0x49800000, v16
	v_rndne_f32_e32 v16, v16
	s_mov_b32 s2, 0x2f800000
	v_mul_f32_e64 v17, |v16|, s2
	v_floor_f32_e32 v17, v17
	s_mov_b32 s2, 0xcf800000
	v_fma_f32 v18, v17, s2, |v16|
	v_cvt_u32_f32_e32 v18, v18
	v_cvt_u32_f32_e32 v17, v17
	v_ashrrev_i32_e32 v19, 31, v16
	v_xor_b32_e32 v16, v18, v19
	v_xor_b32_e32 v17, v17, v19
	v_sub_co_u32_e32 v16, vcc, v16, v19
	s_nop 1
	v_subb_co_u32_e32 v17, vcc, v17, v19, vcc
	global_atomic_add_x2 v[138:139], v[16:17], off offset:1280
.LBB0_293:
	s_or_b64 exec, exec, s[66:67]
	v_lshlrev_b64 v[16:17], 10, v[206:207]
	v_lshl_add_u64 v[18:19], v[16:17], 0, v[204:205]
	v_lshlrev_b32_e32 v20, 16, v84
	v_and_b32_e32 v21, 0xffff0000, v84
	v_lshlrev_b32_e32 v22, 16, v85
	v_and_b32_e32 v23, 0xffff0000, v85
	v_lshlrev_b32_e32 v24, 16, v86
	v_and_b32_e32 v25, 0xffff0000, v86
	v_lshlrev_b32_e32 v26, 16, v87
	v_and_b32_e32 v27, 0xffff0000, v87
	v_pk_add_f32 v[14:15], v[14:15], v[22:23]
	v_pk_add_f32 v[12:13], v[12:13], v[20:21]
	v_pk_add_f32 v[10:11], v[10:11], v[26:27]
	v_pk_add_f32 v[8:9], v[8:9], v[24:25]
	s_and_b64 vcc, exec, s[40:41]
	v_lshl_add_u64 v[18:19], v[18:19], 2, s[48:49]
	s_cbranch_vccnz .LBB0_295
	global_store_dwordx4 v[18:19], v[12:15], off nt
	global_store_dwordx4 v[18:19], v[8:11], off offset:16 nt
.LBB0_295:
	v_cvt_pk_bf16_f32 v20, v12, v13
	v_cvt_pk_bf16_f32 v21, v14, v15
	v_cvt_pk_bf16_f32 v22, v8, v9
	v_cvt_pk_bf16_f32 v23, v10, v11
	v_lshl_add_u64 v[16:17], v[16:17], 1, v[202:203]
	global_store_dwordx4 v[16:17], v[20:23], off nt
	v_lshlrev_b32_e32 v24, 16, v82
	v_and_b32_e32 v25, 0xffff0000, v82
	v_lshlrev_b32_e32 v20, 16, v80
	v_and_b32_e32 v21, 0xffff0000, v80
	v_lshlrev_b32_e32 v22, 16, v81
	v_and_b32_e32 v23, 0xffff0000, v81
	v_lshlrev_b32_e32 v26, 16, v83
	v_and_b32_e32 v27, 0xffff0000, v83
	v_pk_add_f32 v[6:7], v[6:7], v[22:23]
	v_pk_add_f32 v[4:5], v[4:5], v[20:21]
	v_pk_add_f32 v[2:3], v[2:3], v[26:27]
	s_and_b64 vcc, exec, s[40:41]
	v_pk_add_f32 v[0:1], v[0:1], v[24:25]
	s_cbranch_vccnz .LBB0_297
	global_store_dwordx4 v[18:19], v[4:7], off offset:512 nt
	global_store_dwordx4 v[18:19], v[0:3], off offset:528 nt
.LBB0_297:
	v_mul_f32_e32 v13, v13, v13
	v_fmac_f32_e32 v13, v12, v12
	v_mul_f32_e32 v12, v15, v15
	v_fmac_f32_e32 v12, v14, v14
	v_mul_f32_e32 v9, v9, v9
	v_add_f32_e32 v12, v13, v12
	v_fmac_f32_e32 v9, v8, v8
	v_add_f32_e32 v8, v9, v12
	v_mul_f32_e32 v9, v11, v11
	v_fmac_f32_e32 v9, v10, v10
	v_add_f32_e32 v8, v9, v8
	v_mul_f32_e32 v9, v5, v5
	v_mul_f32_e32 v10, v7, v7
	v_fmac_f32_e32 v9, v4, v4
	v_fmac_f32_e32 v10, v6, v6
	v_add_f32_e32 v9, v9, v10
	v_mul_f32_e32 v10, v1, v1
	v_fmac_f32_e32 v10, v0, v0
	v_add_f32_e32 v9, v10, v9
	v_mul_f32_e32 v10, v3, v3
	v_fmac_f32_e32 v10, v2, v2
	v_add_f32_e32 v9, v10, v9
	v_add_f32_e32 v8, v8, v9
	v_cvt_pk_bf16_f32 v4, v4, v5
	v_cvt_pk_bf16_f32 v5, v6, v7
	v_cvt_pk_bf16_f32 v6, v0, v1
	v_mov_b32_e32 v0, v8
	s_nop 1
	v_permlane16_swap_b32_e32 v8, v0
	v_add_f32_e32 v0, v8, v0
	v_mov_b32_e32 v1, v0
	s_nop 1
	v_permlane32_swap_b32_e32 v0, v1
	v_cvt_pk_bf16_f32 v7, v2, v3
	global_store_dwordx4 v[16:17], v[4:7], off offset:256 nt
	s_and_saveexec_b64 s[40:41], s[62:63]
	s_cbranch_execz .LBB0_299
	v_add_f32_e32 v0, v0, v1
	v_mul_f32_e32 v0, 0x49800000, v0
	v_rndne_f32_e32 v0, v0
	s_mov_b32 s2, 0x2f800000
	v_mul_f32_e64 v1, |v0|, s2
	v_floor_f32_e32 v1, v1
	s_mov_b32 s2, 0xcf800000
	v_fma_f32 v2, v1, s2, |v0|
	v_cvt_u32_f32_e32 v2, v2
	v_cvt_u32_f32_e32 v1, v1
	v_ashrrev_i32_e32 v3, 31, v0
	v_xor_b32_e32 v0, v2, v3
	v_xor_b32_e32 v1, v1, v3
	v_sub_co_u32_e32 v0, vcc, v0, v3
	s_nop 1
	v_subb_co_u32_e32 v1, vcc, v1, v3, vcc
	global_atomic_add_x2 v[138:139], v[0:1], off offset:1408
